# v68 variant: the static attention priority raise given to waves 0..3 instead of waves 4..7 (the other half, per the doc's build-both-and-keep-the-faster advice)
# speedup vs baseline: 1.0042x; 1.0042x over previous
.LBB0_1588:
	s_or_b64 exec, exec, s[0:1]
	v_cmp_le_u32_e32 vcc, 0x100, v229
	s_cbranch_vccnz .Latt_prio_done
	s_setprio 1
